# v12 + attention V staging: lane->(row,chunk) assignment changed so each V load instruction covers 16 rows x 64 B (was 64 rows x 16 B); LDS image unchanged
# speedup vs baseline: 1.0086x; 1.0086x over previous
; #define AT_LOADQ(T) do { const size_t tq_ = (T).tb + (size_t)(128 * (T).n + qi) * (T).d; \
;         _Pragma("unroll") for (int k4_ = 0; k4_ < 4; ++k4_) qf[k4_] = *(const bf16x8*)(AQ + tq_ * ATW + (T).head * 128 + k4_ * 32 + 8 * fq); qs = HS[tq_ * 24 + (T).head]; } while (0)
; __device__ __forceinline__ void attn_phase(int wv, const Args& a, LAS unsigned char* lds, int w, bool dmy) {
;     ...
;     const int krow = tid >> 4, kc = tid & 15;
;     const int vc = tid >> 6, vrow = (tid & 63) * 2;
;     const int qi = 16 * wid + fr;
;     u32x4 kr[4], vr[4]; float rk[4]; bf16x8 qf[4]; float qs;
;     ...
;     AttnIt T = attn_decode(12 * w);
;     if (T.n > 0) { AT_LOADBLK(T, T.n - 1); AT_WRITEBLK((T.n & 1) ^ 1); }
;     AT_LOADBLK(T, T.n); AT_LOADQ(T);
.LBB0_646:
	s_or_b64 exec, exec, s[0:1]
	v_readlane_b32 s0, v252, 4
	v_readlane_b32 s1, v252, 5
	s_waitcnt lgkmcnt(0)
	s_barrier
	s_load_dwordx2 s[2:3], s[0:1], 0x88
	v_readlane_b32 s0, v252, 1
	v_mbcnt_lo_u32_b32 v40, -1, 0
	v_mbcnt_hi_u32_b32 v40, -1, v40
	v_readlane_b32 s4, v252, 26
	v_and_b32_e32 v38, 63, v40
	v_or_b32_e32 v39, s0, v40
	s_waitcnt lgkmcnt(0)
	s_add_u32 s0, s2, 0x12100000
	s_addc_u32 s1, s3, 0
	s_add_u32 s13, s2, 0x18100000
	s_addc_u32 s14, s3, 0
	v_ashrrev_i32_e32 v5, 6, v39
	v_and_b32_e32 v85, 15, v40
	s_add_u32 s16, s2, 0x1e100000
	s_waitcnt vmcnt(4)
	v_ashrrev_i32_e32 v89, 4, v39
	v_readlane_b32 s5, v252, 27
	v_readfirstlane_b32 s6, v5
	s_addc_u32 s17, s3, 0
	v_lshrrev_b32_e32 v84, 2, v38
	v_lshlrev_b32_e32 v84, 1, v84
	v_lshrrev_b32_e32 v4, 1, v5
	v_lshl_or_b32 v84, v4, 5, v84
	v_and_b32_e32 v4, 1, v5
	v_and_b32_e32 v5, 3, v38
	v_lshl_or_b32 v5, v4, 2, v5
	s_and_b64 vcc, exec, s[4:5]
	v_lshlrev_b32_e32 v188, 3, v85
	v_lshlrev_b32_e32 v6, 4, v85
	v_lshlrev_b32_e32 v4, 3, v5
	v_mul_lo_u32 v7, v89, s78
	s_cbranch_vccz .LBB0_648
	v_readlane_b32 s4, v252, 31
	v_readlane_b32 s12, v252, 30
	v_readlane_b32 s5, v252, 32
	s_lshl_b64 s[4:5], s[4:5], 1
	v_add_u32_e32 v16, s12, v89
	s_add_u32 s8, s0, s4
	v_ashrrev_i32_e32 v17, 31, v16
	v_readlane_b32 s7, v252, 23
	v_readlane_b32 s10, v252, 24
	s_addc_u32 s9, s1, s5
	v_lshlrev_b32_e32 v32, 4, v85
	v_mov_b32_e32 v33, v189
	v_lshlrev_b64 v[0:1], s7, v[16:17]
	v_readlane_b32 s11, v252, 25
	v_lshl_add_u64 v[22:23], s[8:9], 0, v[32:33]
	s_add_u32 s8, s13, s4
	v_lshl_add_u64 v[0:1], v[0:1], 0, s[10:11]
	s_addc_u32 s9, s14, s5
	v_mad_u64_u32 v[2:3], s[4:5], v0, s80, v[22:23]
	v_mov_b32_e32 v8, v3
	v_mad_u64_u32 v[8:9], s[4:5], v1, s80, v[8:9]
	v_mov_b32_e32 v3, v8
	v_mov_b64_e32 v[24:25], s[16:17]
	global_load_dwordx4 v[8:11], v[2:3], off
	v_mad_u64_u32 v[2:3], s[4:5], v0, s63, v[24:25]
	v_mov_b32_e32 v0, v3
	v_mad_u64_u32 v[0:1], s[4:5], v1, s63, v[0:1]
	v_readlane_b32 s4, v252, 33
	v_readlane_b32 s5, v252, 34
	v_mov_b32_e32 v3, v0
	s_lshl_b64 s[4:5], s[4:5], 2
	v_lshl_add_u64 v[0:1], v[2:3], 0, s[4:5]
	global_load_dword v33, v[0:1], off offset:48
	v_add_u32_e32 v12, 32, v16
	v_ashrrev_i32_e32 v13, 31, v12
	v_lshlrev_b64 v[12:13], s7, v[12:13]
	v_lshl_add_u64 v[12:13], v[12:13], 0, s[10:11]
	v_or_b32_e32 v18, s12, v84
	v_mov_b32_e32 v19, v189
	v_mov_b64_e32 v[20:21], s[8:9]
	v_mad_u64_u32 v[14:15], s[8:9], v12, s80, v[22:23]
	v_lshlrev_b64 v[0:1], s7, v[18:19]
	v_mov_b32_e32 v30, v15
	v_lshl_add_u64 v[0:1], v[0:1], 0, s[10:11]
	v_mad_u64_u32 v[30:31], s[8:9], v13, s80, v[30:31]
	v_mad_u64_u32 v[2:3], s[8:9], v0, s80, v[20:21]
	v_mov_b32_e32 v15, v30
	v_mad_u64_u32 v[30:31], s[8:9], v12, s63, v[24:25]
	v_mov_b32_e32 v0, v3
	v_lshlrev_b32_e32 v34, 3, v5
	v_mov_b32_e32 v12, v31
	v_mad_u64_u32 v[0:1], s[8:9], v1, s80, v[0:1]
	v_ashrrev_i32_e32 v35, 31, v34
	v_mad_u64_u32 v[12:13], s[8:9], v13, s63, v[12:13]
	v_or_b32_e32 v18, 1, v18
	v_mov_b32_e32 v3, v0
	v_lshlrev_b64 v[26:27], 1, v[34:35]
	v_mov_b32_e32 v31, v12
	v_lshlrev_b64 v[18:19], s7, v[18:19]
	v_lshl_add_u64 v[28:29], v[2:3], 0, v[26:27]
	v_lshl_add_u64 v[12:13], v[30:31], 0, s[4:5]
	v_lshl_add_u64 v[18:19], v[18:19], 0, s[10:11]
	global_load_dwordx4 v[0:3], v[28:29], off
	global_load_dword v41, v[12:13], off offset:48
	s_nop 0
	global_load_dwordx4 v[12:15], v[14:15], off
	v_mad_u64_u32 v[30:31], s[8:9], v18, s80, v[20:21]
	v_mov_b32_e32 v18, v31
	v_mad_u64_u32 v[36:37], s[8:9], v19, s80, v[18:19]
	v_add_u32_e32 v18, 64, v16
	v_ashrrev_i32_e32 v19, 31, v18
	v_lshlrev_b64 v[18:19], s7, v[18:19]
	v_lshl_add_u64 v[18:19], v[18:19], 0, s[10:11]
	v_mad_u64_u32 v[42:43], s[8:9], v18, s63, v[24:25]
	v_mad_u64_u32 v[20:21], s[8:9], v18, s80, v[22:23]
	v_mov_b32_e32 v18, v43
	v_mad_u64_u32 v[44:45], s[8:9], v19, s63, v[18:19]
	v_mov_b32_e32 v43, v44
	v_lshl_add_u64 v[42:43], v[42:43], 0, s[4:5]
	global_load_dword v50, v[42:43], off offset:48
	v_add_u32_e32 v16, 0x60, v16
	v_mov_b32_e32 v18, v21
	v_ashrrev_i32_e32 v17, 31, v16
	v_mad_u64_u32 v[18:19], s[8:9], v19, s80, v[18:19]
	v_lshlrev_b64 v[16:17], s7, v[16:17]
	v_mov_b32_e32 v21, v18
	v_lshl_add_u64 v[16:17], v[16:17], 0, s[10:11]
	global_load_dwordx4 v[18:21], v[20:21], off
	v_mad_u64_u32 v[22:23], s[8:9], v16, s80, v[22:23]
	v_mad_u64_u32 v[24:25], s[8:9], v16, s63, v[24:25]
	v_mov_b32_e32 v42, v23
	v_mov_b32_e32 v16, v25
	v_mad_u64_u32 v[42:43], s[8:9], v17, s80, v[42:43]
	v_mad_u64_u32 v[16:17], s[8:9], v17, s63, v[16:17]
	v_mov_b32_e32 v23, v42
	v_mov_b32_e32 v25, v16
	v_lshl_add_u64 v[16:17], v[24:25], 0, s[4:5]
	global_load_dwordx4 v[22:25], v[22:23], off
	s_nop 0
	global_load_dword v51, v[16:17], off offset:48
	v_mov_b32_e32 v31, v36
	v_lshl_add_u64 v[30:31], v[30:31], 0, v[26:27]
	s_waitcnt vmcnt(7)
; __device__ __forceinline__ void attn_phase(int wv, const Args& a, LAS unsigned char* lds, int w, bool dmy) {
;     ...
;     AttnIt T = attn_decode(12 * w);
;     if (T.n > 0) { AT_LOADBLK(T, T.n - 1); AT_WRITEBLK((T.n & 1) ^ 1); }
	v_fmamk_f32 v26, v33, 0x3c000000, v226
	v_mul_f32_e32 v27, 0x4b800000, v26
	v_cmp_gt_f32_e32 vcc, s33, v26
	v_lshlrev_b32_e32 v36, 16, v8
	v_and_b32_e32 v37, 0xffff0000, v8
	v_cndmask_b32_e32 v26, v26, v27, vcc
	v_rsq_f32_e32 v33, v26
	global_load_dwordx4 v[26:29], v[28:29], off offset:128
	s_nop 0
	global_load_dwordx4 v[42:45], v[30:31], off
	global_load_dwordx4 v[46:49], v[30:31], off offset:128
	s_movk_i32 s4, 0x840
	v_add_u32_e32 v16, 64, v34
	v_mul_f32_e32 v30, 0x45800000, v33
	v_cndmask_b32_e32 v30, v33, v30, vcc
	v_pk_mul_f32 v[36:37], v[30:31], v[36:37] op_sel_hi:[0,1]
	v_cvt_pk_bf16_f32 v8, v36, v37
	v_lshlrev_b32_e32 v36, 16, v9
	v_and_b32_e32 v37, 0xffff0000, v9
	v_pk_mul_f32 v[36:37], v[30:31], v[36:37] op_sel_hi:[0,1]
	v_cvt_pk_bf16_f32 v9, v36, v37
	v_lshlrev_b32_e32 v36, 16, v10
	v_and_b32_e32 v37, 0xffff0000, v10
	v_pk_mul_f32 v[36:37], v[30:31], v[36:37] op_sel_hi:[0,1]
	v_cvt_pk_bf16_f32 v10, v36, v37
	v_lshlrev_b32_e32 v36, 16, v11
	v_and_b32_e32 v37, 0xffff0000, v11
	v_pk_mul_f32 v[30:31], v[30:31], v[36:37] op_sel_hi:[0,1]
	v_cvt_pk_bf16_f32 v11, v30, v31
	v_mul_lo_u32 v33, v89, s78
	v_ashrrev_i32_e32 v17, 31, v16
	s_waitcnt vmcnt(8)
	v_fmamk_f32 v30, v41, 0x3c000000, v226
	v_mul_f32_e32 v31, 0x4b800000, v30
	v_cmp_gt_f32_e32 vcc, s33, v30
	v_add_u32_e32 v41, 0x8800, v33
	s_nop 0
	v_cndmask_b32_e32 v30, v30, v31, vcc
	v_rsq_f32_e32 v30, v30
	v_add3_u32 v31, 0, v32, v33
	ds_write_b128 v31, v[8:11] offset:34816
	s_waitcnt vmcnt(7)
	v_and_b32_e32 v9, 0xffff0000, v12
	v_mul_f32_e32 v8, 0x45800000, v30
	v_cndmask_b32_e32 v30, v30, v8, vcc
	v_lshlrev_b32_e32 v8, 16, v12
	v_lshlrev_b32_e32 v10, 16, v13
	v_and_b32_e32 v11, 0xffff0000, v13
	v_pk_mul_f32 v[8:9], v[30:31], v[8:9] op_sel_hi:[0,1]
	v_pk_mul_f32 v[10:11], v[30:31], v[10:11] op_sel_hi:[0,1]
	v_cvt_pk_bf16_f32 v8, v8, v9
	v_cvt_pk_bf16_f32 v9, v10, v11
	v_lshlrev_b32_e32 v10, 16, v14
	v_and_b32_e32 v11, 0xffff0000, v14
	v_pk_mul_f32 v[10:11], v[30:31], v[10:11] op_sel_hi:[0,1]
	v_cvt_pk_bf16_f32 v10, v10, v11
	s_waitcnt vmcnt(6)
	v_fmamk_f32 v11, v50, 0x3c000000, v226
	v_mul_f32_e32 v14, 0x4b800000, v11
	v_cmp_gt_f32_e32 vcc, s33, v11
	v_lshlrev_b32_e32 v12, 16, v15
	v_and_b32_e32 v13, 0xffff0000, v15
	v_cndmask_b32_e32 v11, v11, v14, vcc
	v_rsq_f32_e32 v14, v11
	v_pk_mul_f32 v[12:13], v[30:31], v[12:13] op_sel_hi:[0,1]
	v_cvt_pk_bf16_f32 v11, v12, v13
	ds_write_b128 v31, v[8:11] offset:43520
	v_mul_f32_e32 v8, 0x45800000, v14
	v_cndmask_b32_e32 v12, v14, v8, vcc
	s_waitcnt vmcnt(5)
	v_lshlrev_b32_e32 v8, 16, v18
	v_and_b32_e32 v9, 0xffff0000, v18
	v_lshlrev_b32_e32 v10, 16, v19
	v_and_b32_e32 v11, 0xffff0000, v19
	v_pk_mul_f32 v[8:9], v[12:13], v[8:9] op_sel_hi:[0,1]
	v_pk_mul_f32 v[10:11], v[12:13], v[10:11] op_sel_hi:[0,1]
	v_cvt_pk_bf16_f32 v8, v8, v9
	v_cvt_pk_bf16_f32 v9, v10, v11
	v_lshlrev_b32_e32 v10, 16, v20
	v_and_b32_e32 v11, 0xffff0000, v20
	v_pk_mul_f32 v[10:11], v[12:13], v[10:11] op_sel_hi:[0,1]
	v_cvt_pk_bf16_f32 v10, v10, v11
	s_waitcnt vmcnt(3)
	v_fmamk_f32 v11, v51, 0x3c000000, v226
	v_mul_f32_e32 v13, 0x4b800000, v11
	v_cmp_gt_f32_e32 vcc, s33, v11
	v_lshlrev_b32_e32 v14, 16, v21
	v_and_b32_e32 v15, 0xffff0000, v21
	v_cndmask_b32_e32 v11, v11, v13, vcc
	v_rsq_f32_e32 v18, v11
	v_pk_mul_f32 v[12:13], v[12:13], v[14:15] op_sel_hi:[0,1]
	v_cvt_pk_bf16_f32 v11, v12, v13
	ds_write_b128 v31, v[8:11] offset:52224
	v_mul_f32_e32 v8, 0x45800000, v18
	v_cndmask_b32_e32 v12, v18, v8, vcc
	v_lshlrev_b32_e32 v8, 16, v22
	v_and_b32_e32 v9, 0xffff0000, v22
	v_lshlrev_b32_e32 v10, 16, v23
	v_and_b32_e32 v11, 0xffff0000, v23
	v_pk_mul_f32 v[8:9], v[12:13], v[8:9] op_sel_hi:[0,1]
	v_pk_mul_f32 v[10:11], v[12:13], v[10:11] op_sel_hi:[0,1]
	v_cvt_pk_bf16_f32 v8, v8, v9
	v_cvt_pk_bf16_f32 v9, v10, v11
	v_lshlrev_b32_e32 v10, 16, v24
	v_and_b32_e32 v11, 0xffff0000, v24
	v_lshlrev_b32_e32 v14, 16, v25
	v_and_b32_e32 v15, 0xffff0000, v25
	v_pk_mul_f32 v[10:11], v[12:13], v[10:11] op_sel_hi:[0,1]
	v_pk_mul_f32 v[12:13], v[12:13], v[14:15] op_sel_hi:[0,1]
	v_cvt_pk_bf16_f32 v10, v10, v11
	v_cvt_pk_bf16_f32 v11, v12, v13
	ds_write_b128 v31, v[8:11] offset:60928
	v_mad_u64_u32 v[8:9], s[4:5], v5, s4, v[84:85]
	v_lshl_add_u32 v5, v8, 1, 0
	v_and_b32_e32 v8, 0xffff, v0
	v_lshrrev_b32_e32 v0, 16, v0
	s_mov_b32 s4, 0xffff0000
	v_add_u32_e32 v5, 0x11100, v5
	s_waitcnt vmcnt(1)
	v_lshl_or_b32 v8, v42, 16, v8
	v_and_or_b32 v0, v42, s4, v0
	ds_write2_b32 v5, v8, v0 offset1:132
	v_and_b32_e32 v0, 0xffff, v1
	v_lshrrev_b32_e32 v1, 16, v1
	v_lshl_or_b32 v0, v43, 16, v0
	v_and_or_b32 v1, v43, s4, v1
	v_add_u32_e32 v8, 0x400, v5
	ds_write2_b32 v8, v0, v1 offset0:8 offset1:140
	v_and_b32_e32 v0, 0xffff, v2
	v_lshrrev_b32_e32 v1, 16, v2
	v_lshl_or_b32 v0, v44, 16, v0
	v_and_or_b32 v1, v44, s4, v1
	v_add_u32_e32 v2, 0x800, v5
	ds_write2_b32 v2, v0, v1 offset0:16 offset1:148
	v_and_b32_e32 v0, 0xffff, v3
	v_lshrrev_b32_e32 v1, 16, v3
	v_lshl_or_b32 v0, v45, 16, v0
	v_and_or_b32 v1, v45, s4, v1
	v_add_u32_e32 v2, 0xc00, v5
	ds_write2_b32 v2, v0, v1 offset0:24 offset1:156
	v_and_b32_e32 v0, 0xffff, v26
	v_lshrrev_b32_e32 v1, 16, v26
	s_waitcnt vmcnt(0)
	v_lshl_or_b32 v0, v46, 16, v0
	v_and_or_b32 v1, v46, s4, v1
	v_add_u32_e32 v2, 0x8400, v5
	ds_write2_b32 v2, v0, v1 offset1:132
	v_and_b32_e32 v0, 0xffff, v27
	v_lshrrev_b32_e32 v1, 16, v27
	v_lshl_or_b32 v0, v47, 16, v0
	v_and_or_b32 v1, v47, s4, v1
	v_add_u32_e32 v2, 0x8800, v5
	ds_write2_b32 v2, v0, v1 offset0:8 offset1:140
	v_and_b32_e32 v0, 0xffff, v28
	v_lshrrev_b32_e32 v1, 16, v28
	v_lshl_or_b32 v0, v48, 16, v0
	v_and_or_b32 v1, v48, s4, v1
	v_add_u32_e32 v2, 0x8c00, v5
	ds_write2_b32 v2, v0, v1 offset0:16 offset1:148
	v_and_b32_e32 v0, 0xffff, v29
	v_lshrrev_b32_e32 v1, 16, v29
	v_lshl_or_b32 v0, v49, 16, v0
	v_and_or_b32 v1, v49, s4, v1
	v_add_u32_e32 v2, 0x9000, v5
	ds_write2_b32 v2, v0, v1 offset0:24 offset1:156
	s_mov_b64 s[4:5], 0
	v_mov_b64_e32 v[0:1], v[34:35]
	s_branch .LBB0_649
